# kvhwait: window-attention kv-head head waits vmcnt(2) for kvh>0 (output stores stay in flight), on top of v63
# baseline (speedup 1.0000x reference)
; #define LBAR() do { asm volatile("s_waitcnt lgkmcnt(0)" ::: "memory"); __builtin_amdgcn_s_barrier(); asm volatile("" ::: "memory"); } while (0)
; __device__ __forceinline__ void mixer_unit(const Params& p, LAS unsigned char* lds, int tile, int layer, int wave_s) {
;     ...
;         for (int kvh = 0; kvh < 4; ++kvh) {
;             const int hq = kvh * 4 + (wave >> 1), rhalf = (wave & 1) * 64;
;             LBAR();
.LBB0_481:
	s_waitcnt lgkmcnt(0)
	s_barrier
	s_cmp_eq_u32 s72, 0
	s_cbranch_scc1 .Lwa_head_first
	s_waitcnt vmcnt(2)
	s_branch .Lwa_head_go

; #define LAS __attribute__((address_space(3)))
; #define LBAR() do { asm volatile("s_waitcnt lgkmcnt(0)" ::: "memory"); __builtin_amdgcn_s_barrier(); asm volatile("" ::: "memory"); } while (0)
; __device__ __forceinline__ int slot_of(int kappa) { const int kq = kappa & 31; return (kappa & ~31) + 16 * ((kq >> 2) & 1) + 4 * (kq >> 3) + (kq & 3); }
; __device__ __forceinline__ void mixer_unit(const Params& p, LAS unsigned char* lds, int tile, int layer, int wave_s) {
;     ...
; #pragma unroll
;             for (int j = 0; j < 6; ++j) {
;                 const int idx = tid + NTHREADS * j, kap = idx >> 3, ch = idx & 7;
;                 const int sl = slot_of(kap);
;                 *(LAS u32x4*)(lds + L_K + sl * 128 + ((ch ^ (sl & 7)) << 4)) = kreg[j];
;                 const int fk = (kap & 3) | (((kap >> 3) & 1) << 2);
;                 *(LAS u32x4*)(lds + L_VT + kap * 128 + ((ch ^ fk) << 4)) = vreg[j];
;             }
;             LBAR();
;     ...
;             if (kvh < 3) WIN_PREFETCH(kvh + 1);
.Lwa_head_go:
	ds_write_b128 v167, v[8:11]
	ds_write_b128 v168, v[4:7] offset:49152
	ds_write_b128 v169, v[16:19]
	ds_write_b128 v170, v[12:15] offset:49152
	ds_write_b128 v171, v[24:27]
	ds_write_b128 v172, v[20:23] offset:49152
	ds_write_b128 v173, v[32:35]
	ds_write_b128 v174, v[28:31] offset:49152
	ds_write_b128 v175, v[40:43]
	ds_write_b128 v176, v[36:39] offset:49152
	ds_write_b128 v177, v[56:59]
	ds_write_b128 v178, v[52:55] offset:49152
	s_waitcnt lgkmcnt(0)
	s_barrier
	s_cmp_eq_u32 s72, 3
	s_cbranch_scc1 .LBB0_495
	v_mov_b32_e32 v12, v0
	v_mov_b32_e32 v13, v0
	v_mov_b32_e32 v14, v0
	v_mov_b32_e32 v15, v0
	v_mov_b64_e32 v[4:5], v[12:13]
	v_mov_b64_e32 v[8:9], v[12:13]
	v_lshl_add_u32 v60, s72, 6, v141
	v_mov_b64_e32 v[6:7], v[14:15]
	v_mov_b64_e32 v[10:11], v[14:15]
	s_and_saveexec_b64 s[10:11], s[22:23]
	s_cbranch_execz .LBB0_484
	v_add_lshl_u32 v1, v60, v132, 1
	v_add_u32_e32 v2, 0x1000, v1
	v_add_u32_e32 v1, 0x1200, v1
	global_load_dwordx4 v[4:7], v1, s[16:17]
	global_load_dwordx4 v[8:11], v2, s[16:17]
